# mlp1 epilogue hand-written: lane halves of each 16-lane row exchange their two column chunks (DPP row_ror:8) so each store instruction writes eight full 128-byte row segments instead of sixteen 64-byt
# speedup vs baseline: 1.0616x; 1.0076x over previous
;     DI void operator()(const Acc& acc, const Unit& u, int wr, int wc, int fr, int fq) const {
;         const int row0 = u.pm * BM + wr * 64 + fr, col0 = u.pn * BM + wc * 64 + 8 * fq;
; #pragma unroll
;         for (int ai = 0; ai < 2; ++ai)
; #pragma unroll
;             for (int m = 0; m < 4; ++m) {
;                 bf16_t* rp = U + (size_t)(row0 + ai * HALF + m * 16) * 4096 + col0;
; #pragma unroll
;                 for (int bj = 0; bj < 2; ++bj) {
;                     f32x4 a = acc[ai][bj][m][0], b = acc[ai][bj][m][1];
; #pragma unroll
;                     for (int j = 0; j < 4; ++j) { a[j] = a[j] > 0.f ? a[j] * a[j] : 0.f; b[j] = b[j] > 0.f ? b[j] * b[j] : 0.f; }
;                     u32x4 o; o[0] = pk_bf16(a[0], a[1]); o[1] = pk_bf16(a[2], a[3]); o[2] = pk_bf16(b[0], b[1]); o[3] = pk_bf16(b[2], b[3]);
;                     *(u32x4*)(rp + bj * 32) = o;
;                 }
.LBB0_155:
	v_lshl_add_u32 v136, s66, 8, v140
	v_ashrrev_i32_e32 v137, 31, v136
	v_lshl_or_b32 v134, s67, 8, v142
	v_lshlrev_b64 v[138:139], 13, v[136:137]
	v_readlane_b32 s36, v254, 27
	v_ashrrev_i32_e32 v135, 31, v134
	v_readlane_b32 s37, v254, 28
	v_lshl_add_u64 v[144:145], s[36:37], 0, v[138:139]
	v_lshlrev_b64 v[138:139], 1, v[134:135]
	v_lshl_add_u64 v[134:135], v[144:145], 0, v[138:139]
	s_mov_b64 s[54:55], 0x100000
	s_mov_b32 s67, s64
	s_mov_b32 s66, s65
	s_mov_b64 s[56:57], s[52:53]
	v_and_b32_e32 v192, 8, v174
	v_mov_b32_e32 v193, 0xffff0040
	v_cmp_ne_u32_e32 vcc, 0, v192
	v_mov_b32_e32 v194, 0x10000
	v_mov_b32_e32 v195, 0
	v_cndmask_b32_e32 v192, 0, v193, vcc
	v_cndmask_b32_e64 v193, 0, -1, vcc
	v_lshl_add_u64 v[196:197], v[134:135], 0, v[192:193]
	v_max_f32_e32 v120, 0, v120
	v_max_f32_e32 v121, 0, v121
	v_max_f32_e32 v122, 0, v122
	v_max_f32_e32 v123, 0, v123
	v_max_f32_e32 v124, 0, v124
	v_max_f32_e32 v125, 0, v125
	v_max_f32_e32 v126, 0, v126
	v_max_f32_e32 v127, 0, v127
	v_pk_mul_f32 v[120:121], v[120:121], v[120:121]
	v_pk_mul_f32 v[122:123], v[122:123], v[122:123]
	v_pk_mul_f32 v[124:125], v[124:125], v[124:125]
	v_pk_mul_f32 v[126:127], v[126:127], v[126:127]
	v_cvt_pk_bf16_f32 v123, v122, v123
	v_cvt_pk_bf16_f32 v122, v120, v121
	v_cvt_pk_bf16_f32 v121, v126, v127
	v_cvt_pk_bf16_f32 v120, v124, v125
	v_max_f32_e32 v112, 0, v112
	v_max_f32_e32 v113, 0, v113
	v_max_f32_e32 v114, 0, v114
	v_max_f32_e32 v115, 0, v115
	v_max_f32_e32 v116, 0, v116
	v_max_f32_e32 v117, 0, v117
	v_max_f32_e32 v118, 0, v118
	v_max_f32_e32 v119, 0, v119
	v_pk_mul_f32 v[112:113], v[112:113], v[112:113]
	v_pk_mul_f32 v[114:115], v[114:115], v[114:115]
	v_pk_mul_f32 v[116:117], v[116:117], v[116:117]
	v_pk_mul_f32 v[118:119], v[118:119], v[118:119]
	v_cvt_pk_bf16_f32 v115, v114, v115
	v_cvt_pk_bf16_f32 v114, v112, v113
	v_cvt_pk_bf16_f32 v113, v118, v119
	v_cvt_pk_bf16_f32 v112, v116, v117
	v_mov_b64_e32 v[198:199], v[196:197]
	v_lshl_add_u64 v[200:201], v[198:199], 0, v[194:195]
	v_mov_b32_dpp v204, v120 row_ror:8 row_mask:0xf bank_mask:0x3
	v_mov_b32_dpp v205, v121 row_ror:8 row_mask:0xf bank_mask:0x3
	v_mov_b32_dpp v206, v122 row_ror:8 row_mask:0xf bank_mask:0x3
	v_mov_b32_dpp v207, v123 row_ror:8 row_mask:0xf bank_mask:0x3
	v_mov_b32_dpp v120, v112 row_ror:8 row_mask:0xf bank_mask:0xc
	v_mov_b32_dpp v121, v113 row_ror:8 row_mask:0xf bank_mask:0xc
	v_mov_b32_dpp v122, v114 row_ror:8 row_mask:0xf bank_mask:0xc
	v_mov_b32_dpp v123, v115 row_ror:8 row_mask:0xf bank_mask:0xc
	v_mov_b32_dpp v112, v204 quad_perm:[0,1,2,3] row_mask:0xf bank_mask:0x3
	v_mov_b32_dpp v113, v205 quad_perm:[0,1,2,3] row_mask:0xf bank_mask:0x3
	v_mov_b32_dpp v114, v206 quad_perm:[0,1,2,3] row_mask:0xf bank_mask:0x3
	v_mov_b32_dpp v115, v207 quad_perm:[0,1,2,3] row_mask:0xf bank_mask:0x3
	global_store_dwordx4 v[198:199], v[120:123], off
	global_store_dwordx4 v[200:201], v[112:115], off
	s_nop 1
	v_max_f32_e32 v104, 0, v104
	v_max_f32_e32 v105, 0, v105
	v_max_f32_e32 v106, 0, v106
	v_max_f32_e32 v107, 0, v107
	v_max_f32_e32 v108, 0, v108
	v_max_f32_e32 v109, 0, v109
	v_max_f32_e32 v110, 0, v110
	v_max_f32_e32 v111, 0, v111
	v_pk_mul_f32 v[104:105], v[104:105], v[104:105]
	v_pk_mul_f32 v[106:107], v[106:107], v[106:107]
	v_pk_mul_f32 v[108:109], v[108:109], v[108:109]
	v_pk_mul_f32 v[110:111], v[110:111], v[110:111]
	v_cvt_pk_bf16_f32 v107, v106, v107
	v_cvt_pk_bf16_f32 v106, v104, v105
	v_cvt_pk_bf16_f32 v105, v110, v111
	v_cvt_pk_bf16_f32 v104, v108, v109
	v_max_f32_e32 v96, 0, v96
	v_max_f32_e32 v97, 0, v97
	v_max_f32_e32 v98, 0, v98
	v_max_f32_e32 v99, 0, v99
	v_max_f32_e32 v100, 0, v100
	v_max_f32_e32 v101, 0, v101
	v_max_f32_e32 v102, 0, v102
	v_max_f32_e32 v103, 0, v103
	v_pk_mul_f32 v[96:97], v[96:97], v[96:97]
	v_pk_mul_f32 v[98:99], v[98:99], v[98:99]
	v_pk_mul_f32 v[100:101], v[100:101], v[100:101]
	v_pk_mul_f32 v[102:103], v[102:103], v[102:103]
	v_cvt_pk_bf16_f32 v99, v98, v99
	v_cvt_pk_bf16_f32 v98, v96, v97
	v_cvt_pk_bf16_f32 v97, v102, v103
	v_cvt_pk_bf16_f32 v96, v100, v101
	s_mov_b64 s[54:55], 0x20000
	v_lshl_add_u64 v[198:199], v[196:197], 0, s[54:55]
	v_lshl_add_u64 v[200:201], v[198:199], 0, v[194:195]
	v_mov_b32_dpp v204, v104 row_ror:8 row_mask:0xf bank_mask:0x3
	v_mov_b32_dpp v205, v105 row_ror:8 row_mask:0xf bank_mask:0x3
	v_mov_b32_dpp v206, v106 row_ror:8 row_mask:0xf bank_mask:0x3
	v_mov_b32_dpp v207, v107 row_ror:8 row_mask:0xf bank_mask:0x3
	v_mov_b32_dpp v104, v96 row_ror:8 row_mask:0xf bank_mask:0xc
	v_mov_b32_dpp v105, v97 row_ror:8 row_mask:0xf bank_mask:0xc
	v_mov_b32_dpp v106, v98 row_ror:8 row_mask:0xf bank_mask:0xc
	v_mov_b32_dpp v107, v99 row_ror:8 row_mask:0xf bank_mask:0xc
	v_mov_b32_dpp v96, v204 quad_perm:[0,1,2,3] row_mask:0xf bank_mask:0x3
	v_mov_b32_dpp v97, v205 quad_perm:[0,1,2,3] row_mask:0xf bank_mask:0x3
	v_mov_b32_dpp v98, v206 quad_perm:[0,1,2,3] row_mask:0xf bank_mask:0x3
	v_mov_b32_dpp v99, v207 quad_perm:[0,1,2,3] row_mask:0xf bank_mask:0x3
	global_store_dwordx4 v[198:199], v[104:107], off
	global_store_dwordx4 v[200:201], v[96:99], off
	s_nop 1
	v_max_f32_e32 v88, 0, v88
	v_max_f32_e32 v89, 0, v89
	v_max_f32_e32 v90, 0, v90
	v_max_f32_e32 v91, 0, v91
	v_max_f32_e32 v92, 0, v92
	v_max_f32_e32 v93, 0, v93
	v_max_f32_e32 v94, 0, v94
	v_max_f32_e32 v95, 0, v95
	v_pk_mul_f32 v[88:89], v[88:89], v[88:89]
	v_pk_mul_f32 v[90:91], v[90:91], v[90:91]
	v_pk_mul_f32 v[92:93], v[92:93], v[92:93]
	v_pk_mul_f32 v[94:95], v[94:95], v[94:95]
	v_cvt_pk_bf16_f32 v91, v90, v91
	v_cvt_pk_bf16_f32 v90, v88, v89
	v_cvt_pk_bf16_f32 v89, v94, v95
	v_cvt_pk_bf16_f32 v88, v92, v93
	v_max_f32_e32 v80, 0, v80
	v_max_f32_e32 v81, 0, v81
;     DI void operator()(const Acc& acc, const Unit& u, int wr, int wc, int fr, int fq) const {
;         const int row0 = u.pm * BM + wr * 64 + fr, col0 = u.pn * BM + wc * 64 + 8 * fq;
; #pragma unroll
;         for (int ai = 0; ai < 2; ++ai)
; #pragma unroll
;             for (int m = 0; m < 4; ++m) {
;                 bf16_t* rp = U + (size_t)(row0 + ai * HALF + m * 16) * 4096 + col0;
; #pragma unroll
;                 for (int bj = 0; bj < 2; ++bj) {
;                     f32x4 a = acc[ai][bj][m][0], b = acc[ai][bj][m][1];
; #pragma unroll
;                     for (int j = 0; j < 4; ++j) { a[j] = a[j] > 0.f ? a[j] * a[j] : 0.f; b[j] = b[j] > 0.f ? b[j] * b[j] : 0.f; }
;                     u32x4 o; o[0] = pk_bf16(a[0], a[1]); o[1] = pk_bf16(a[2], a[3]); o[2] = pk_bf16(b[0], b[1]); o[3] = pk_bf16(b[2], b[3]);
;                     *(u32x4*)(rp + bj * 32) = o;
;                 }
	v_max_f32_e32 v82, 0, v82
	v_max_f32_e32 v83, 0, v83
	v_max_f32_e32 v84, 0, v84
	v_max_f32_e32 v85, 0, v85
	v_max_f32_e32 v86, 0, v86
	v_max_f32_e32 v87, 0, v87
	v_pk_mul_f32 v[80:81], v[80:81], v[80:81]
	v_pk_mul_f32 v[82:83], v[82:83], v[82:83]
	v_pk_mul_f32 v[84:85], v[84:85], v[84:85]
	v_pk_mul_f32 v[86:87], v[86:87], v[86:87]
	v_cvt_pk_bf16_f32 v83, v82, v83
	v_cvt_pk_bf16_f32 v82, v80, v81
	v_cvt_pk_bf16_f32 v81, v86, v87
	v_cvt_pk_bf16_f32 v80, v84, v85
	s_mov_b64 s[54:55], 0x40000
	v_lshl_add_u64 v[198:199], v[196:197], 0, s[54:55]
	v_lshl_add_u64 v[200:201], v[198:199], 0, v[194:195]
	v_mov_b32_dpp v204, v88 row_ror:8 row_mask:0xf bank_mask:0x3
	v_mov_b32_dpp v205, v89 row_ror:8 row_mask:0xf bank_mask:0x3
	v_mov_b32_dpp v206, v90 row_ror:8 row_mask:0xf bank_mask:0x3
	v_mov_b32_dpp v207, v91 row_ror:8 row_mask:0xf bank_mask:0x3
	v_mov_b32_dpp v88, v80 row_ror:8 row_mask:0xf bank_mask:0xc
	v_mov_b32_dpp v89, v81 row_ror:8 row_mask:0xf bank_mask:0xc
	v_mov_b32_dpp v90, v82 row_ror:8 row_mask:0xf bank_mask:0xc
	v_mov_b32_dpp v91, v83 row_ror:8 row_mask:0xf bank_mask:0xc
	v_mov_b32_dpp v80, v204 quad_perm:[0,1,2,3] row_mask:0xf bank_mask:0x3
	v_mov_b32_dpp v81, v205 quad_perm:[0,1,2,3] row_mask:0xf bank_mask:0x3
	v_mov_b32_dpp v82, v206 quad_perm:[0,1,2,3] row_mask:0xf bank_mask:0x3
	v_mov_b32_dpp v83, v207 quad_perm:[0,1,2,3] row_mask:0xf bank_mask:0x3
	global_store_dwordx4 v[198:199], v[88:91], off
	global_store_dwordx4 v[200:201], v[80:83], off
	s_nop 1
	v_max_f32_e32 v72, 0, v72
	v_max_f32_e32 v73, 0, v73
	v_max_f32_e32 v74, 0, v74
	v_max_f32_e32 v75, 0, v75
	v_max_f32_e32 v76, 0, v76
	v_max_f32_e32 v77, 0, v77
	v_max_f32_e32 v78, 0, v78
	v_max_f32_e32 v79, 0, v79
	v_pk_mul_f32 v[72:73], v[72:73], v[72:73]
	v_pk_mul_f32 v[74:75], v[74:75], v[74:75]
	v_pk_mul_f32 v[76:77], v[76:77], v[76:77]
	v_pk_mul_f32 v[78:79], v[78:79], v[78:79]
	v_cvt_pk_bf16_f32 v75, v74, v75
	v_cvt_pk_bf16_f32 v74, v72, v73
	v_cvt_pk_bf16_f32 v73, v78, v79
	v_cvt_pk_bf16_f32 v72, v76, v77
	v_max_f32_e32 v64, 0, v64
	v_max_f32_e32 v65, 0, v65
	v_max_f32_e32 v66, 0, v66
	v_max_f32_e32 v67, 0, v67
	v_max_f32_e32 v68, 0, v68
	v_max_f32_e32 v69, 0, v69
	v_max_f32_e32 v70, 0, v70
	v_max_f32_e32 v71, 0, v71
	v_pk_mul_f32 v[64:65], v[64:65], v[64:65]
	v_pk_mul_f32 v[66:67], v[66:67], v[66:67]
	v_pk_mul_f32 v[68:69], v[68:69], v[68:69]
	v_pk_mul_f32 v[70:71], v[70:71], v[70:71]
	v_cvt_pk_bf16_f32 v67, v66, v67
	v_cvt_pk_bf16_f32 v66, v64, v65
	v_cvt_pk_bf16_f32 v65, v70, v71
	v_cvt_pk_bf16_f32 v64, v68, v69
	s_mov_b64 s[54:55], 0x60000
	v_lshl_add_u64 v[198:199], v[196:197], 0, s[54:55]
	v_lshl_add_u64 v[200:201], v[198:199], 0, v[194:195]
	v_mov_b32_dpp v204, v72 row_ror:8 row_mask:0xf bank_mask:0x3
	v_mov_b32_dpp v205, v73 row_ror:8 row_mask:0xf bank_mask:0x3
	v_mov_b32_dpp v206, v74 row_ror:8 row_mask:0xf bank_mask:0x3
	v_mov_b32_dpp v207, v75 row_ror:8 row_mask:0xf bank_mask:0x3
	v_mov_b32_dpp v72, v64 row_ror:8 row_mask:0xf bank_mask:0xc
	v_mov_b32_dpp v73, v65 row_ror:8 row_mask:0xf bank_mask:0xc
	v_mov_b32_dpp v74, v66 row_ror:8 row_mask:0xf bank_mask:0xc
	v_mov_b32_dpp v75, v67 row_ror:8 row_mask:0xf bank_mask:0xc
	v_mov_b32_dpp v64, v204 quad_perm:[0,1,2,3] row_mask:0xf bank_mask:0x3
	v_mov_b32_dpp v65, v205 quad_perm:[0,1,2,3] row_mask:0xf bank_mask:0x3
	v_mov_b32_dpp v66, v206 quad_perm:[0,1,2,3] row_mask:0xf bank_mask:0x3
	v_mov_b32_dpp v67, v207 quad_perm:[0,1,2,3] row_mask:0xf bank_mask:0x3
	global_store_dwordx4 v[198:199], v[72:75], off
	global_store_dwordx4 v[200:201], v[64:67], off
	s_nop 1
	v_max_f32_e32 v56, 0, v56
	v_max_f32_e32 v57, 0, v57
	v_max_f32_e32 v58, 0, v58
	v_max_f32_e32 v59, 0, v59
	v_max_f32_e32 v60, 0, v60
	v_max_f32_e32 v61, 0, v61
	v_max_f32_e32 v62, 0, v62
	v_max_f32_e32 v63, 0, v63
	v_pk_mul_f32 v[56:57], v[56:57], v[56:57]
	v_pk_mul_f32 v[58:59], v[58:59], v[58:59]
	v_pk_mul_f32 v[60:61], v[60:61], v[60:61]
	v_pk_mul_f32 v[62:63], v[62:63], v[62:63]
	v_cvt_pk_bf16_f32 v59, v58, v59
	v_cvt_pk_bf16_f32 v58, v56, v57
	v_cvt_pk_bf16_f32 v57, v62, v63
	v_cvt_pk_bf16_f32 v56, v60, v61
	v_max_f32_e32 v48, 0, v48
	v_max_f32_e32 v49, 0, v49
	v_max_f32_e32 v50, 0, v50
	v_max_f32_e32 v51, 0, v51
	v_max_f32_e32 v52, 0, v52
	v_max_f32_e32 v53, 0, v53
	v_max_f32_e32 v54, 0, v54
	v_max_f32_e32 v55, 0, v55
	v_pk_mul_f32 v[48:49], v[48:49], v[48:49]
	v_pk_mul_f32 v[50:51], v[50:51], v[50:51]
	v_pk_mul_f32 v[52:53], v[52:53], v[52:53]
	v_pk_mul_f32 v[54:55], v[54:55], v[54:55]
	v_cvt_pk_bf16_f32 v51, v50, v51
	v_cvt_pk_bf16_f32 v50, v48, v49
	v_cvt_pk_bf16_f32 v49, v54, v55
	v_cvt_pk_bf16_f32 v48, v52, v53
	s_mov_b64 s[54:55], 0x100000
	v_lshl_add_u64 v[198:199], v[196:197], 0, s[54:55]
	v_lshl_add_u64 v[200:201], v[198:199], 0, v[194:195]
	v_mov_b32_dpp v204, v56 row_ror:8 row_mask:0xf bank_mask:0x3
	v_mov_b32_dpp v205, v57 row_ror:8 row_mask:0xf bank_mask:0x3
	v_mov_b32_dpp v206, v58 row_ror:8 row_mask:0xf bank_mask:0x3
	v_mov_b32_dpp v207, v59 row_ror:8 row_mask:0xf bank_mask:0x3
	v_mov_b32_dpp v56, v48 row_ror:8 row_mask:0xf bank_mask:0xc
	v_mov_b32_dpp v57, v49 row_ror:8 row_mask:0xf bank_mask:0xc
	v_mov_b32_dpp v58, v50 row_ror:8 row_mask:0xf bank_mask:0xc
	v_mov_b32_dpp v59, v51 row_ror:8 row_mask:0xf bank_mask:0xc
	v_mov_b32_dpp v48, v204 quad_perm:[0,1,2,3] row_mask:0xf bank_mask:0x3
	v_mov_b32_dpp v49, v205 quad_perm:[0,1,2,3] row_mask:0xf bank_mask:0x3
	v_mov_b32_dpp v50, v206 quad_perm:[0,1,2,3] row_mask:0xf bank_mask:0x3
	v_mov_b32_dpp v51, v207 quad_perm:[0,1,2,3] row_mask:0xf bank_mask:0x3
	global_store_dwordx4 v[198:199], v[56:59], off
	global_store_dwordx4 v[200:201], v[48:51], off
	s_nop 1
	v_max_f32_e32 v40, 0, v40
;     DI void operator()(const Acc& acc, const Unit& u, int wr, int wc, int fr, int fq) const {
;         const int row0 = u.pm * BM + wr * 64 + fr, col0 = u.pn * BM + wc * 64 + 8 * fq;
; #pragma unroll
;         for (int ai = 0; ai < 2; ++ai)
; #pragma unroll
;             for (int m = 0; m < 4; ++m) {
;                 bf16_t* rp = U + (size_t)(row0 + ai * HALF + m * 16) * 4096 + col0;
; #pragma unroll
;                 for (int bj = 0; bj < 2; ++bj) {
;                     f32x4 a = acc[ai][bj][m][0], b = acc[ai][bj][m][1];
; #pragma unroll
;                     for (int j = 0; j < 4; ++j) { a[j] = a[j] > 0.f ? a[j] * a[j] : 0.f; b[j] = b[j] > 0.f ? b[j] * b[j] : 0.f; }
;                     u32x4 o; o[0] = pk_bf16(a[0], a[1]); o[1] = pk_bf16(a[2], a[3]); o[2] = pk_bf16(b[0], b[1]); o[3] = pk_bf16(b[2], b[3]);
;                     *(u32x4*)(rp + bj * 32) = o;
;                 }
	v_max_f32_e32 v41, 0, v41
	v_max_f32_e32 v42, 0, v42
	v_max_f32_e32 v43, 0, v43
	v_max_f32_e32 v44, 0, v44
	v_max_f32_e32 v45, 0, v45
	v_max_f32_e32 v46, 0, v46
	v_max_f32_e32 v47, 0, v47
	v_pk_mul_f32 v[40:41], v[40:41], v[40:41]
	v_pk_mul_f32 v[42:43], v[42:43], v[42:43]
	v_pk_mul_f32 v[44:45], v[44:45], v[44:45]
	v_pk_mul_f32 v[46:47], v[46:47], v[46:47]
	v_cvt_pk_bf16_f32 v43, v42, v43
	v_cvt_pk_bf16_f32 v42, v40, v41
	v_cvt_pk_bf16_f32 v41, v46, v47
	v_cvt_pk_bf16_f32 v40, v44, v45
	v_max_f32_e32 v32, 0, v32
	v_max_f32_e32 v33, 0, v33
	v_max_f32_e32 v34, 0, v34
	v_max_f32_e32 v35, 0, v35
	v_max_f32_e32 v36, 0, v36
	v_max_f32_e32 v37, 0, v37
	v_max_f32_e32 v38, 0, v38
	v_max_f32_e32 v39, 0, v39
	v_pk_mul_f32 v[32:33], v[32:33], v[32:33]
	v_pk_mul_f32 v[34:35], v[34:35], v[34:35]
	v_pk_mul_f32 v[36:37], v[36:37], v[36:37]
	v_pk_mul_f32 v[38:39], v[38:39], v[38:39]
	v_cvt_pk_bf16_f32 v35, v34, v35
	v_cvt_pk_bf16_f32 v34, v32, v33
	v_cvt_pk_bf16_f32 v33, v38, v39
	v_cvt_pk_bf16_f32 v32, v36, v37
	s_mov_b64 s[54:55], 0x120000
	v_lshl_add_u64 v[198:199], v[196:197], 0, s[54:55]
	v_lshl_add_u64 v[200:201], v[198:199], 0, v[194:195]
	v_mov_b32_dpp v204, v40 row_ror:8 row_mask:0xf bank_mask:0x3
	v_mov_b32_dpp v205, v41 row_ror:8 row_mask:0xf bank_mask:0x3
	v_mov_b32_dpp v206, v42 row_ror:8 row_mask:0xf bank_mask:0x3
	v_mov_b32_dpp v207, v43 row_ror:8 row_mask:0xf bank_mask:0x3
	v_mov_b32_dpp v40, v32 row_ror:8 row_mask:0xf bank_mask:0xc
	v_mov_b32_dpp v41, v33 row_ror:8 row_mask:0xf bank_mask:0xc
	v_mov_b32_dpp v42, v34 row_ror:8 row_mask:0xf bank_mask:0xc
	v_mov_b32_dpp v43, v35 row_ror:8 row_mask:0xf bank_mask:0xc
	v_mov_b32_dpp v32, v204 quad_perm:[0,1,2,3] row_mask:0xf bank_mask:0x3
	v_mov_b32_dpp v33, v205 quad_perm:[0,1,2,3] row_mask:0xf bank_mask:0x3
	v_mov_b32_dpp v34, v206 quad_perm:[0,1,2,3] row_mask:0xf bank_mask:0x3
	v_mov_b32_dpp v35, v207 quad_perm:[0,1,2,3] row_mask:0xf bank_mask:0x3
	global_store_dwordx4 v[198:199], v[40:43], off
	global_store_dwordx4 v[200:201], v[32:35], off
	s_nop 1
	v_max_f32_e32 v24, 0, v24
	v_max_f32_e32 v25, 0, v25
	v_max_f32_e32 v26, 0, v26
	v_max_f32_e32 v27, 0, v27
	v_max_f32_e32 v28, 0, v28
	v_max_f32_e32 v29, 0, v29
	v_max_f32_e32 v30, 0, v30
	v_max_f32_e32 v31, 0, v31
	v_pk_mul_f32 v[24:25], v[24:25], v[24:25]
	v_pk_mul_f32 v[26:27], v[26:27], v[26:27]
	v_pk_mul_f32 v[28:29], v[28:29], v[28:29]
	v_pk_mul_f32 v[30:31], v[30:31], v[30:31]
	v_cvt_pk_bf16_f32 v27, v26, v27
	v_cvt_pk_bf16_f32 v26, v24, v25
	v_cvt_pk_bf16_f32 v25, v30, v31
	v_cvt_pk_bf16_f32 v24, v28, v29
	v_max_f32_e32 v16, 0, v16
	v_max_f32_e32 v17, 0, v17
	v_max_f32_e32 v18, 0, v18
	v_max_f32_e32 v19, 0, v19
	v_max_f32_e32 v20, 0, v20
	v_max_f32_e32 v21, 0, v21
	v_max_f32_e32 v22, 0, v22
	v_max_f32_e32 v23, 0, v23
	v_pk_mul_f32 v[16:17], v[16:17], v[16:17]
	v_pk_mul_f32 v[18:19], v[18:19], v[18:19]
	v_pk_mul_f32 v[20:21], v[20:21], v[20:21]
	v_pk_mul_f32 v[22:23], v[22:23], v[22:23]
	v_cvt_pk_bf16_f32 v19, v18, v19
	v_cvt_pk_bf16_f32 v18, v16, v17
	v_cvt_pk_bf16_f32 v17, v22, v23
	v_cvt_pk_bf16_f32 v16, v20, v21
	s_mov_b64 s[54:55], 0x140000
	v_lshl_add_u64 v[198:199], v[196:197], 0, s[54:55]
	v_lshl_add_u64 v[200:201], v[198:199], 0, v[194:195]
	v_mov_b32_dpp v204, v24 row_ror:8 row_mask:0xf bank_mask:0x3
	v_mov_b32_dpp v205, v25 row_ror:8 row_mask:0xf bank_mask:0x3
	v_mov_b32_dpp v206, v26 row_ror:8 row_mask:0xf bank_mask:0x3
	v_mov_b32_dpp v207, v27 row_ror:8 row_mask:0xf bank_mask:0x3
	v_mov_b32_dpp v24, v16 row_ror:8 row_mask:0xf bank_mask:0xc
	v_mov_b32_dpp v25, v17 row_ror:8 row_mask:0xf bank_mask:0xc
	v_mov_b32_dpp v26, v18 row_ror:8 row_mask:0xf bank_mask:0xc
	v_mov_b32_dpp v27, v19 row_ror:8 row_mask:0xf bank_mask:0xc
	v_mov_b32_dpp v16, v204 quad_perm:[0,1,2,3] row_mask:0xf bank_mask:0x3
	v_mov_b32_dpp v17, v205 quad_perm:[0,1,2,3] row_mask:0xf bank_mask:0x3
	v_mov_b32_dpp v18, v206 quad_perm:[0,1,2,3] row_mask:0xf bank_mask:0x3
	v_mov_b32_dpp v19, v207 quad_perm:[0,1,2,3] row_mask:0xf bank_mask:0x3
	global_store_dwordx4 v[198:199], v[24:27], off
	global_store_dwordx4 v[200:201], v[16:19], off
	s_nop 1
	v_max_f32_e32 v8, 0, v8
	v_max_f32_e32 v9, 0, v9
	v_max_f32_e32 v10, 0, v10
	v_max_f32_e32 v11, 0, v11
	v_max_f32_e32 v12, 0, v12
	v_max_f32_e32 v13, 0, v13
	v_max_f32_e32 v14, 0, v14
	v_max_f32_e32 v15, 0, v15
	v_pk_mul_f32 v[8:9], v[8:9], v[8:9]
	v_pk_mul_f32 v[10:11], v[10:11], v[10:11]
	v_pk_mul_f32 v[12:13], v[12:13], v[12:13]
	v_pk_mul_f32 v[14:15], v[14:15], v[14:15]
	v_cvt_pk_bf16_f32 v11, v10, v11
	v_cvt_pk_bf16_f32 v10, v8, v9
	v_cvt_pk_bf16_f32 v9, v14, v15
	v_cvt_pk_bf16_f32 v8, v12, v13
	v_max_f32_e32 v0, 0, v0
	v_max_f32_e32 v1, 0, v1
	v_max_f32_e32 v2, 0, v2
	v_max_f32_e32 v3, 0, v3
	v_max_f32_e32 v4, 0, v4
	v_max_f32_e32 v5, 0, v5
	v_max_f32_e32 v6, 0, v6
	v_max_f32_e32 v7, 0, v7
	v_pk_mul_f32 v[0:1], v[0:1], v[0:1]
	v_pk_mul_f32 v[2:3], v[2:3], v[2:3]
	v_pk_mul_f32 v[4:5], v[4:5], v[4:5]
	v_pk_mul_f32 v[6:7], v[6:7], v[6:7]
	v_cvt_pk_bf16_f32 v3, v2, v3
	v_cvt_pk_bf16_f32 v2, v0, v1
	v_cvt_pk_bf16_f32 v1, v6, v7
	v_cvt_pk_bf16_f32 v0, v4, v5
	s_mov_b64 s[54:55], 0x160000
	v_lshl_add_u64 v[198:199], v[196:197], 0, s[54:55]
	v_lshl_add_u64 v[200:201], v[198:199], 0, v[194:195]
	v_mov_b32_dpp v204, v8 row_ror:8 row_mask:0xf bank_mask:0x3
	v_mov_b32_dpp v205, v9 row_ror:8 row_mask:0xf bank_mask:0x3
	v_mov_b32_dpp v206, v10 row_ror:8 row_mask:0xf bank_mask:0x3
	v_mov_b32_dpp v207, v11 row_ror:8 row_mask:0xf bank_mask:0x3
	v_mov_b32_dpp v8, v0 row_ror:8 row_mask:0xf bank_mask:0xc
	v_mov_b32_dpp v9, v1 row_ror:8 row_mask:0xf bank_mask:0xc
	v_mov_b32_dpp v10, v2 row_ror:8 row_mask:0xf bank_mask:0xc
	v_mov_b32_dpp v11, v3 row_ror:8 row_mask:0xf bank_mask:0xc
	v_mov_b32_dpp v0, v204 quad_perm:[0,1,2,3] row_mask:0xf bank_mask:0x3
	v_mov_b32_dpp v1, v205 quad_perm:[0,1,2,3] row_mask:0xf bank_mask:0x3
	v_mov_b32_dpp v2, v206 quad_perm:[0,1,2,3] row_mask:0xf bank_mask:0x3
	v_mov_b32_dpp v3, v207 quad_perm:[0,1,2,3] row_mask:0xf bank_mask:0x3
	global_store_dwordx4 v[198:199], v[8:11], off
	global_store_dwordx4 v[200:201], v[0:3], off
	s_nop 1
	s_mov_b64 s[54:55], s[12:13]
	s_and_b64 vcc, exec, s[10:11]
	s_cbranch_vccnz .LBB0_169
